# NA lat-item prologue: first K/V tile loads issued right after Q loads, before Q scaling (on top of GQA+MLA tile-0 hoists)
# baseline (speedup 1.0000x reference)
.LBB0_199:
	s_or_b64 exec, exec, s[8:9]
	s_ashr_i32 s8, s2, 9
	s_lshr_b32 s9, s2, 2
	s_and_b32 s24, s9, 0x7c
	s_mulk_i32 s8, 0x2100
	s_add_i32 s25, s8, 0x100
	s_lshl_b32 s9, s24, 6
	s_add_i32 s34, s25, s9
	s_ashr_i32 s35, s34, 31
	s_lshl_b64 s[34:35], s[34:35], 13
	s_add_u32 s34, s89, s34
	s_addc_u32 s35, s26, s35
	s_lshl_b32 s9, s92, 7
	s_add_u32 s38, s34, s9
	s_addc_u32 s39, s35, 0
	v_lshl_add_u64 v[2:3], s[38:39], 0, v[110:111]
	v_mov_b32_e32 v107, v1
	v_lshl_add_u64 v[14:15], v[2:3], 0, v[106:107]
	global_load_dwordx4 v[2:5], v[14:15], off
	global_load_dwordx4 v[6:9], v[14:15], off offset:32
	global_load_dwordx4 v[10:13], v[14:15], off offset:64
	s_nop 0
	global_load_dwordx4 v[14:17], v[14:15], off offset:96
	s_add_u32 vcc_lo, s27, s9
	s_addc_u32 vcc_hi, s28, 0
	s_add_u32 s74, s29, s9
	s_addc_u32 s75, s36, 0
	s_ashr_i32 s9, s8, 31
	v_lshl_add_u64 v[104:105], s[8:9], 0, v[114:115]
	v_lshlrev_b64 v[104:105], 13, v[104:105]
	v_lshl_add_u64 v[100:101], vcc, 0, v[104:105]
	v_lshl_add_u64 v[104:105], s[74:75], 0, v[104:105]
	v_lshl_add_u64 v[104:105], v[104:105], 0, v[0:1]
	v_lshl_add_u64 v[100:101], v[100:101], 0, v[0:1]
	global_load_dwordx4 v[104:107], v[104:105], off
	global_load_dwordx4 v[100:103], v[100:101], off
	s_nop 0
	s_nop 0
	s_nop 0
	s_nop 0
	s_cmp_lt_i32 s73, 1
	s_waitcnt vmcnt(5)
	v_lshlrev_b32_e32 v18, 16, v2
	v_and_b32_e32 v2, 0xffff0000, v2
	v_lshlrev_b32_e32 v19, 16, v3
	v_and_b32_e32 v3, 0xffff0000, v3
	v_lshlrev_b32_e32 v20, 16, v4
	v_and_b32_e32 v4, 0xffff0000, v4
	v_mul_f32_e32 v2, 0x3e38aa3b, v2
	v_mul_f32_e32 v3, 0x3e38aa3b, v3
	v_mul_f32_e32 v18, 0x3e38aa3b, v18
	v_mul_f32_e32 v19, 0x3e38aa3b, v19
	v_mul_f32_e32 v4, 0x3e38aa3b, v4
	v_cvt_pk_bf16_f32 v84, v18, v2
	v_cvt_pk_bf16_f32 v85, v19, v3
	s_waitcnt vmcnt(2)
	v_and_b32_e32 v2, 0xffff0000, v16
	v_lshlrev_b32_e32 v3, 16, v17
	v_lshlrev_b32_e32 v21, 16, v5
	v_and_b32_e32 v5, 0xffff0000, v5
	v_lshlrev_b32_e32 v22, 16, v6
	v_and_b32_e32 v6, 0xffff0000, v6
	v_lshlrev_b32_e32 v23, 16, v7
	v_and_b32_e32 v7, 0xffff0000, v7
	v_lshlrev_b32_e32 v24, 16, v8
	v_and_b32_e32 v8, 0xffff0000, v8
	v_lshlrev_b32_e32 v25, 16, v9
	v_and_b32_e32 v9, 0xffff0000, v9
	v_lshlrev_b32_e32 v26, 16, v10
	v_and_b32_e32 v10, 0xffff0000, v10
	v_lshlrev_b32_e32 v27, 16, v11
	v_and_b32_e32 v11, 0xffff0000, v11
	v_lshlrev_b32_e32 v28, 16, v12
	v_and_b32_e32 v12, 0xffff0000, v12
	v_lshlrev_b32_e32 v29, 16, v13
	v_and_b32_e32 v13, 0xffff0000, v13
	v_lshlrev_b32_e32 v30, 16, v14
	v_and_b32_e32 v14, 0xffff0000, v14
	v_lshlrev_b32_e32 v31, 16, v15
	v_and_b32_e32 v15, 0xffff0000, v15
	v_lshlrev_b32_e32 v32, 16, v16
	v_mul_f32_e32 v20, 0x3e38aa3b, v20
	v_cvt_pk_bf16_f32 v86, v20, v4
	v_mul_f32_e32 v2, 0x3e38aa3b, v2
	v_mul_f32_e32 v3, 0x3e38aa3b, v3
	v_and_b32_e32 v4, 0xffff0000, v17
	v_mul_f32_e32 v21, 0x3e38aa3b, v21
	v_mul_f32_e32 v5, 0x3e38aa3b, v5
	v_mul_f32_e32 v22, 0x3e38aa3b, v22
	v_mul_f32_e32 v6, 0x3e38aa3b, v6
	v_mul_f32_e32 v23, 0x3e38aa3b, v23
	v_mul_f32_e32 v7, 0x3e38aa3b, v7
	v_mul_f32_e32 v24, 0x3e38aa3b, v24
	v_mul_f32_e32 v8, 0x3e38aa3b, v8
	v_mul_f32_e32 v25, 0x3e38aa3b, v25
	v_mul_f32_e32 v9, 0x3e38aa3b, v9
	v_mul_f32_e32 v26, 0x3e38aa3b, v26
	v_mul_f32_e32 v10, 0x3e38aa3b, v10
	v_mul_f32_e32 v27, 0x3e38aa3b, v27
	v_mul_f32_e32 v11, 0x3e38aa3b, v11
	v_mul_f32_e32 v28, 0x3e38aa3b, v28
	v_mul_f32_e32 v12, 0x3e38aa3b, v12
	v_mul_f32_e32 v29, 0x3e38aa3b, v29
	v_mul_f32_e32 v13, 0x3e38aa3b, v13
	v_mul_f32_e32 v30, 0x3e38aa3b, v30
	v_mul_f32_e32 v14, 0x3e38aa3b, v14
	v_mul_f32_e32 v31, 0x3e38aa3b, v31
	v_mul_f32_e32 v15, 0x3e38aa3b, v15
	v_mul_f32_e32 v32, 0x3e38aa3b, v32
	v_cvt_pk_bf16_f32 v87, v21, v5
	v_cvt_pk_bf16_f32 v88, v22, v6
	v_cvt_pk_bf16_f32 v89, v23, v7
	v_cvt_pk_bf16_f32 v90, v24, v8
	v_cvt_pk_bf16_f32 v91, v25, v9
	v_cvt_pk_bf16_f32 v92, v26, v10
	v_cvt_pk_bf16_f32 v93, v27, v11
	v_cvt_pk_bf16_f32 v94, v28, v12
	v_cvt_pk_bf16_f32 v95, v29, v13
	v_mul_f32_e32 v4, 0x3e38aa3b, v4
	v_cvt_pk_bf16_f32 v96, v30, v14
	v_cvt_pk_bf16_f32 v97, v31, v15
	v_cvt_pk_bf16_f32 v98, v32, v2
	v_cvt_pk_bf16_f32 v99, v3, v4
	v_lshl_add_u64 v[2:3], s[8:9], 0, v[114:115]
	v_lshlrev_b64 v[2:3], 13, v[2:3]
	v_lshl_add_u64 v[4:5], vcc, 0, v[2:3]
	v_lshl_add_u64 v[2:3], s[74:75], 0, v[2:3]
	v_lshl_add_u64 v[2:3], v[2:3], 0, v[0:1]
	v_lshl_add_u64 v[4:5], v[4:5], 0, v[0:1]
	s_waitcnt vmcnt(0)
	s_waitcnt vmcnt(1)
	ds_write_b128 v113, v[104:107]
	s_waitcnt vmcnt(0)
	ds_write_b128 v117, v[100:103] offset:16384
	s_waitcnt lgkmcnt(0)
	s_barrier
	s_cbranch_scc1 .LBB0_252
	s_cmp_lg_u32 s73, 1
	v_lshl_add_u64 v[124:125], vcc, 0, v[0:1]
	s_cselect_b64 vcc, -1, 0
	s_cmp_eq_u32 s73, 1
	v_lshl_add_u64 v[126:127], s[74:75], 0, v[0:1]
	s_cbranch_scc1 .LBB0_202
	s_or_b32 s38, s8, 64
	s_ashr_i32 s39, s38, 31
	v_lshl_add_u64 v[2:3], s[38:39], 0, v[114:115]
	v_lshlrev_b64 v[2:3], 13, v[2:3]
	v_lshl_add_u64 v[4:5], v[124:125], 0, v[2:3]
	v_lshl_add_u64 v[2:3], v[126:127], 0, v[2:3]
	global_load_dwordx4 v[100:103], v[4:5], off
	global_load_dwordx4 v[104:107], v[2:3], off

.LBB0_267:
	s_mov_b64 s[4:5], -1
	s_nop 0
	s_nop 0
	s_nop 0
	s_nop 0
	s_nop 0
	s_nop 0
	s_nop 0
	s_nop 0
	s_nop 0
	s_nop 0
	s_nop 0
	s_nop 0
	s_nop 0
	s_nop 0
	s_nop 0
	s_nop 0
	s_nop 0
	s_nop 0
	s_nop 0
	s_nop 0
	s_nop 0
	s_nop 0
	s_nop 0
	s_nop 0
	s_nop 0
	s_nop 0
	s_nop 0
	s_nop 0
	s_nop 0
	s_nop 0
	s_nop 0
	s_nop 0
	s_nop 0
	s_nop 0
	s_nop 0
	s_nop 0
	s_nop 0
	s_nop 0
	s_nop 0
	s_nop 0
	s_nop 0
	s_nop 0
	s_nop 0
	s_nop 0
	s_nop 0
	s_nop 0
	s_nop 0
	s_nop 0
	s_nop 0
	s_nop 0
	s_nop 0
	s_nop 0
	s_nop 0
	s_nop 0
	s_nop 0
	s_nop 0
	s_nop 0
	s_nop 0
	s_nop 0
	s_nop 0
	s_nop 0
	s_nop 0
	s_nop 0
	s_nop 0
	s_nop 0
	s_nop 0
	s_nop 0
	s_nop 0
	s_nop 0
	s_nop 0
	s_nop 0
	s_nop 0
	s_nop 0
	s_nop 0
	s_nop 0
	s_nop 0
	s_nop 0
	s_nop 0
	s_nop 0
	s_nop 0
	s_nop 0
	s_nop 0
	s_nop 0
	s_nop 0
	s_nop 0
	s_nop 0
	s_nop 0
	s_nop 0
	s_nop 0
	s_nop 0
	s_nop 0
	s_nop 0
	s_nop 0
	s_nop 0
	s_nop 0
	s_nop 0
	s_nop 0
	s_nop 0
	s_nop 0
	s_nop 0
	s_nop 0
